# P6 SwiGLU epilogue rstd loads hoisted; MLA 2nd-tile QK K-fragment reads double-buffered with counted lgkmcnt; code placement of that segment shifted by 4 bytes
# speedup vs baseline: 1.0120x; 1.0120x over previous
; #define LAS __attribute__((address_space(3)))
; __device__ __forceinline__ void finishSM(f32x16& p0, f32x16& p1, float alpha, float& l_reg, bf16x8& pa0, bf16x8& pa1, bf16x8& pa2, bf16x8& pa3) {
; #pragma unroll
;     for (int r = 0; r < 16; ++r) p1[r] = __builtin_amdgcn_exp2f(p1[r]);
;     typedef float f32x2 __attribute__((ext_vector_type(2)));
;     f32x2 s2 = (f32x2){p0[0], p0[1]};
; #pragma unroll
;     for (int r = 2; r < 16; r += 2) s2 += (f32x2){p0[r], p0[r + 1]};
; #pragma unroll
;     for (int r = 0; r < 16; r += 2) s2 += (f32x2){p1[r], p1[r + 1]};
;     float ps = s2.x + s2.y;
;     { auto rr = __builtin_amdgcn_permlane32_swap(__float_as_uint(ps), __float_as_uint(ps), false, false);
;       ps = __uint_as_float(rr[0]) + __uint_as_float(rr[1]); }
;     l_reg = l_reg * alpha + ps;
;     ...
;     PK4(p0, 0, pa0); PK4(p0, 8, pa1); PK4(p1, 0, pa2); PK4(p1, 8, pa3);
;     ...
; }
; template <int MODE> __device__ __forceinline__ void qkt(f32x16& p0, f32x16& p1, const LAS unsigned char* Kt, const LAS unsigned char* Krt, const bf16x8* qr, int r32, int hi, int comp) {
;     p0 = f32x16{}; p1 = f32x16{};
;     constexpr int NDN = MODE ? 8 : 4;
; #pragma unroll
;     for (int d0 = 0; d0 < NDN; ++d0) { const int cb = ((MODE ? 0 : comp * 64) + d0 * 16 + hi * 8) * 2;
;         const bf16x8 b0 = *(const LAS bf16x8*)(Kt + KSWZ(r32, cb));
;         const bf16x8 b1 = *(const LAS bf16x8*)(Kt + KSWZ(32 + r32, cb));
;         p0 = __builtin_amdgcn_mfma_f32_32x32x16_bf16(b0, qr[d0], p0, 0, 0, 0);
;         p1 = __builtin_amdgcn_mfma_f32_32x32x16_bf16(b1, qr[d0], p1, 0, 0, 0); }
;     if constexpr (MODE == 1) {
; #pragma unroll
;         for (int d0 = 0; d0 < 4; ++d0) { const int cb = (d0 * 16 + hi * 8) * 2;
;             const bf16x8 b0 = *(const LAS bf16x8*)(Krt + KRSWZ(r32, cb));
;             const bf16x8 b1 = *(const LAS bf16x8*)(Krt + KRSWZ(32 + r32, cb));
;             p0 = __builtin_amdgcn_mfma_f32_32x32x16_bf16(b0, qr[8 + d0], p0, 0, 0, 0);
;             p1 = __builtin_amdgcn_mfma_f32_32x32x16_bf16(b1, qr[8 + d0], p1, 0, 0, 0); }
;     }
; }
.LBB0_614:
	s_nop 0
	ds_read_b128 v[80:83], v205 offset:49152
	ds_read_b128 v[84:87], v205 offset:57344
	ds_read_b128 v[248:251], v207 offset:49152
	ds_read_b128 v[198:201], v207 offset:57344
	ds_read_b128 v[234:237], v209 offset:49152
	ds_read_b128 v[238:241], v209 offset:57344
	v_exp_f32_e32 v112, v112
	v_exp_f32_e32 v113, v113
	s_waitcnt lgkmcnt(4)
	v_mfma_f32_32x32x16_bf16 v[96:111], v[80:83], v[172:175], 0
	v_exp_f32_e32 v114, v114
	v_exp_f32_e32 v115, v115
	v_exp_f32_e32 v122, v122
	v_exp_f32_e32 v123, v123
	v_exp_f32_e32 v124, v124
	v_exp_f32_e32 v125, v125
	v_exp_f32_e32 v126, v126
	v_mfma_f32_32x32x16_bf16 v[80:95], v[84:87], v[172:175], 0
	v_exp_f32_e32 v127, v127
	s_waitcnt lgkmcnt(2)
	v_mfma_f32_32x32x16_bf16 v[96:111], v[248:251], v[168:171], v[96:111]
	v_mfma_f32_32x32x16_bf16 v[80:95], v[198:201], v[168:171], v[80:95]
	ds_read_b128 v[198:201], v211 offset:49152
	ds_read_b128 v[248:251], v211 offset:57344
	s_waitcnt lgkmcnt(2)
	v_mfma_f32_32x32x16_bf16 v[96:111], v[234:237], v[164:167], v[96:111]
	v_mfma_f32_32x32x16_bf16 v[80:95], v[238:241], v[164:167], v[80:95]
	ds_read_b128 v[234:237], v213 offset:49152
	ds_read_b128 v[238:241], v213 offset:57344
	s_waitcnt lgkmcnt(2)
	v_mfma_f32_32x32x16_bf16 v[96:111], v[198:201], v[160:163], v[96:111]
	v_mfma_f32_32x32x16_bf16 v[80:95], v[248:251], v[160:163], v[80:95]
	ds_read_b128 v[198:201], v215 offset:49152
	ds_read_b128 v[248:251], v215 offset:57344
	s_waitcnt lgkmcnt(2)
	v_mfma_f32_32x32x16_bf16 v[96:111], v[234:237], v[156:159], v[96:111]
	v_mfma_f32_32x32x16_bf16 v[80:95], v[238:241], v[156:159], v[80:95]
	ds_read_b128 v[234:237], v217 offset:49152
	ds_read_b128 v[238:241], v217 offset:57344
	s_waitcnt lgkmcnt(2)
	v_mfma_f32_32x32x16_bf16 v[96:111], v[198:201], v[152:155], v[96:111]
	v_mfma_f32_32x32x16_bf16 v[80:95], v[248:251], v[152:155], v[80:95]
	ds_read_b128 v[198:201], v219 offset:49152
	ds_read_b128 v[248:251], v219 offset:57344
	s_waitcnt lgkmcnt(2)
	v_mfma_f32_32x32x16_bf16 v[96:111], v[234:237], v[148:151], v[96:111]
	v_mfma_f32_32x32x16_bf16 v[80:95], v[238:241], v[148:151], v[80:95]
	ds_read_b128 v[234:237], v221
	ds_read_b128 v[238:241], v221 offset:4096
	s_waitcnt lgkmcnt(2)
	v_mfma_f32_32x32x16_bf16 v[96:111], v[198:201], v[144:147], v[96:111]
	v_mfma_f32_32x32x16_bf16 v[80:95], v[248:251], v[144:147], v[80:95]
	ds_read_b128 v[198:201], v223
	ds_read_b128 v[248:251], v223 offset:4096
	s_waitcnt lgkmcnt(2)
	v_mfma_f32_32x32x16_bf16 v[96:111], v[234:237], v[140:143], v[96:111]
	v_mfma_f32_32x32x16_bf16 v[80:95], v[238:241], v[140:143], v[80:95]
	ds_read_b128 v[234:237], v225
	ds_read_b128 v[238:241], v225 offset:4096
	s_waitcnt lgkmcnt(2)
	v_mfma_f32_32x32x16_bf16 v[96:111], v[198:201], v[136:139], v[96:111]
	v_mfma_f32_32x32x16_bf16 v[80:95], v[248:251], v[136:139], v[80:95]
	ds_read_b128 v[198:201], v227
	ds_read_b128 v[248:251], v227 offset:4096
	s_waitcnt lgkmcnt(2)
	v_mfma_f32_32x32x16_bf16 v[96:111], v[234:237], v[132:135], v[96:111]
	v_mfma_f32_32x32x16_bf16 v[80:95], v[238:241], v[132:135], v[80:95]
	s_waitcnt lgkmcnt(0)
	v_mfma_f32_32x32x16_bf16 v[96:111], v[198:201], v[128:131], v[96:111]
	v_exp_f32_e32 v198, v116
	v_exp_f32_e32 v199, v117
	v_pk_add_f32 v[116:117], v[64:65], v[66:67]
	v_exp_f32_e32 v200, v118
	v_pk_add_f32 v[116:117], v[68:69], v[116:117]
	v_exp_f32_e32 v201, v119
	v_pk_add_f32 v[116:117], v[70:71], v[116:117]
	v_mfma_f32_32x32x16_bf16 v[80:95], v[248:251], v[128:131], v[80:95]
	v_add_f32_e64 v116, v72, v116
	v_add_f32_e64 v117, v73, v117
	v_exp_f32_e32 v248, v120
	v_pk_add_f32 v[116:117], v[74:75], v[116:117]
	v_exp_f32_e32 v249, v121
	v_pk_add_f32 v[116:117], v[76:77], v[116:117]
	s_nop 0
	v_pk_add_f32 v[116:117], v[78:79], v[116:117]
	s_nop 0
	v_pk_add_f32 v[116:117], v[112:113], v[116:117]
	s_nop 0
	v_pk_add_f32 v[116:117], v[114:115], v[116:117]
	s_nop 0
	v_pk_add_f32 v[116:117], v[198:199], v[116:117]
	s_nop 0
	v_pk_add_f32 v[116:117], v[200:201], v[116:117]
	s_nop 0
	v_pk_add_f32 v[116:117], v[248:249], v[116:117]
	s_nop 0
	v_pk_add_f32 v[116:117], v[122:123], v[116:117]
	s_nop 0
	v_pk_add_f32 v[116:117], v[124:125], v[116:117]
	s_nop 0
	v_pk_add_f32 v[116:117], v[126:127], v[116:117]
	s_nop 0
	v_pk_add_f32 v[120:121], v[116:117], v[116:117] op_sel:[0,1] op_sel_hi:[1,0]
	v_cvt_pk_bf16_f32 v116, v64, v65
	v_cvt_pk_bf16_f32 v117, v66, v67
	v_cvt_pk_bf16_f32 v118, v68, v69
	v_cvt_pk_bf16_f32 v119, v70, v71
	v_cvt_pk_bf16_f32 v72, v72, v73
	s_nop 0
	v_mov_b32_e32 v121, v120
	v_cvt_pk_bf16_f32 v73, v74, v75
	v_cvt_pk_bf16_f32 v74, v76, v77
	v_cvt_pk_bf16_f32 v75, v78, v79
	v_cvt_pk_bf16_f32 v76, v112, v113
	v_cvt_pk_bf16_f32 v77, v114, v115
	v_cvt_pk_bf16_f32 v78, v198, v199
	v_cvt_pk_bf16_f32 v79, v200, v201
	v_cvt_pk_bf16_f32 v112, v248, v249
	v_cvt_pk_bf16_f32 v113, v122, v123
	v_cvt_pk_bf16_f32 v114, v124, v125
	v_cvt_pk_bf16_f32 v115, v126, v127
	s_nop 1
	v_permlane32_swap_b32_e32 v120, v121
	s_and_b64 vcc, exec, s[4:5]
	s_cbranch_vccnz .LBB0_616
	s_waitcnt vmcnt(0) lgkmcnt(0)
	s_barrier
; #define SBAR() __builtin_amdgcn_sched_barrier(0)
; #define LW(n) asm volatile("s_waitcnt lgkmcnt(" #n ")" ::: "memory")
; template <int MODE, bool PF> __device__ __forceinline__ void pv_partial(f32x16* o, int vb, bf16x8 pa0, bf16x8 pa1, bf16x8 pa2, bf16x8 pa3, f32x16& p0, f32x16& p1, float& m_reg, float& alpha) {
;     VFrag fa, fb;
;     v_frag_read<0>(fa, vb);
;     if constexpr (PF) { v_frag_read<1>(fb, vb); LW(8); } else LW(0);
;     SBAR();
;     pv_mma(o[0], fa, pa0, pa1, pa2, pa3);
;     float pm0 = p0[0];
; #pragma unroll
;     for (int r = 1; r < 16; ++r) pm0 = fmaxf(pm0, p0[r]);
;     if constexpr (PF) { v_frag_read<2>(fa, vb); LW(8); } else { v_frag_read<1>(fb, vb); LW(0); }
;     SBAR();
;     pv_mma(o[1], fb, pa0, pa1, pa2, pa3);
;     float pmax = pm0;
; #pragma unroll
;     for (int r = 0; r < 16; ++r) pmax = fmaxf(pmax, p1[r]);
;     { auto rr = __builtin_amdgcn_permlane32_swap(__float_as_uint(pmax), __float_as_uint(pmax), false, false);
;       pmax = fmaxf(__uint_as_float(rr[0]), __uint_as_float(rr[1])); }
;     const float mn = (pmax - m_reg > Cst<MODE>::THRS) ? fmaxf(m_reg, pmax) : m_reg;
;     alpha = __builtin_amdgcn_exp2f(m_reg - mn); m_reg = mn;
;     const f32x16 mnv = {mn, mn, mn, mn, mn, mn, mn, mn, mn, mn, mn, mn, mn, mn, mn, mn};
;     if constexpr (PF) { v_frag_read<3>(fb, vb); LW(8); } else { v_frag_read<2>(fa, vb); LW(0); }
;     SBAR();
;     pv_mma(o[2], fa, pa0, pa1, pa2, pa3);
;     p0 = p0 - mnv; p1 = p1 - mnv;
; #pragma unroll
;     for (int r = 0; r < 8; ++r) p0[r] = __builtin_amdgcn_exp2f(p0[r]);
;     if constexpr (PF) { LW(0); } else { v_frag_read<3>(fb, vb); LW(0); }
;     SBAR();
;     pv_mma(o[3], fb, pa0, pa1, pa2, pa3);
; #pragma unroll
;     for (int r = 8; r < 16; ++r) p0[r] = __builtin_amdgcn_exp2f(p0[r]);
;     asm volatile("" : "+v"(p0), "+v"(p1));
; }
.LBB0_616:
	s_nop 0
	v_add_u32_e32 v126, s83, v203
	ds_read_b64_tr_b16 v[64:65], v126 offset:0
	ds_read_b64_tr_b16 v[66:67], v126 offset:0x800
	ds_read_b64_tr_b16 v[68:69], v126 offset:0x1000
	ds_read_b64_tr_b16 v[70:71], v126 offset:0x1800
	ds_read_b64_tr_b16 v[122:123], v126 offset:0x2000
	ds_read_b64_tr_b16 v[124:125], v126 offset:0x2800
	ds_read_b64_tr_b16 v[198:199], v126 offset:0x3000
	ds_read_b64_tr_b16 v[200:201], v126 offset:0x3800
	s_waitcnt lgkmcnt(0)
	s_nop 0
	v_mfma_f32_32x32x16_bf16 v[0:15], v[116:119], v[64:67], v[0:15]
	v_max_f32_e32 v64, v97, v97
	v_max_f32_e32 v65, v96, v96
	v_max_f32_e32 v64, v65, v64
	v_max3_f32 v64, v64, v98, v99
	v_max3_f32 v64, v64, v100, v101
	v_max3_f32 v64, v64, v102, v103
	v_max3_f32 v64, v64, v104, v105
	v_mfma_f32_32x32x16_bf16 v[0:15], v[72:75], v[68:71], v[0:15]
	v_max3_f32 v64, v64, v106, v107
	v_max3_f32 v64, v64, v108, v109
	v_max3_f32 v127, v64, v110, v111
	ds_read_b64_tr_b16 v[64:65], v126 offset:0x200
	ds_read_b64_tr_b16 v[66:67], v126 offset:0xa00
	ds_read_b64_tr_b16 v[68:69], v126 offset:0x1200
	ds_read_b64_tr_b16 v[70:71], v126 offset:0x1a00
	v_mfma_f32_32x32x16_bf16 v[0:15], v[76:79], v[122:125], v[0:15]
	ds_read_b64_tr_b16 v[122:123], v126 offset:0x2200
	ds_read_b64_tr_b16 v[124:125], v126 offset:0x2a00
	v_mfma_f32_32x32x16_bf16 v[0:15], v[112:115], v[198:201], v[0:15]
	ds_read_b64_tr_b16 v[198:199], v126 offset:0x3200
	ds_read_b64_tr_b16 v[200:201], v126 offset:0x3a00
	s_waitcnt lgkmcnt(0)
	v_mfma_f32_32x32x16_bf16 v[48:63], v[116:119], v[64:67], v[48:63]
	v_max3_f32 v64, v127, v80, v81
	v_max3_f32 v64, v64, v82, v83
	v_max3_f32 v64, v64, v84, v85
	v_max3_f32 v64, v64, v86, v87
	v_max3_f32 v64, v64, v88, v89
	v_max3_f32 v64, v64, v90, v91
	v_max3_f32 v64, v64, v92, v93
	v_mfma_f32_32x32x16_bf16 v[48:63], v[72:75], v[68:71], v[48:63]
	v_max3_f32 v64, v64, v94, v95
	v_mov_b32_e32 v65, v64
	s_nop 1
	v_permlane32_swap_b32_e32 v64, v65
	v_max_f32_e32 v65, v65, v65
	v_max_f32_e32 v64, v64, v64
	v_max_f32_e32 v64, v64, v65
	v_mfma_f32_32x32x16_bf16 v[48:63], v[76:79], v[122:125], v[48:63]
	v_sub_f32_e32 v65, v64, v244
	v_cmp_lt_f32_e32 vcc, s78, v65
	v_max_f32_e32 v65, v244, v244
	v_max_f32_e32 v64, v65, v64
	v_cndmask_b32_e32 v243, v244, v64, vcc
	v_sub_f32_e32 v64, v244, v243
	v_exp_f32_e32 v244, v64
	ds_read_b64_tr_b16 v[64:65], v126 offset:0x400
	ds_read_b64_tr_b16 v[66:67], v126 offset:0xc00
	ds_read_b64_tr_b16 v[68:69], v126 offset:0x1400
	v_mfma_f32_32x32x16_bf16 v[48:63], v[112:115], v[198:201], v[48:63]
	ds_read_b64_tr_b16 v[70:71], v126 offset:0x1c00
	ds_read_b64_tr_b16 v[122:123], v126 offset:0x2400
	ds_read_b64_tr_b16 v[124:125], v126 offset:0x2c00
	ds_read_b64_tr_b16 v[198:199], v126 offset:0x3400
	ds_read_b64_tr_b16 v[200:201], v126 offset:0x3c00
	s_waitcnt lgkmcnt(0)
	v_mfma_f32_32x32x16_bf16 v[32:47], v[116:119], v[64:67], v[32:47]
	v_sub_f32_e32 v65, v97, v243
	v_sub_f32_e32 v64, v96, v243
	ds_read_b64_tr_b16 v[96:97], v126 offset:0x600
	v_sub_f32_e32 v67, v99, v243
	v_sub_f32_e32 v66, v98, v243
	ds_read_b64_tr_b16 v[98:99], v126 offset:0xe00
	v_sub_f32_e32 v127, v107, v243
	v_mfma_f32_32x32x16_bf16 v[32:47], v[72:75], v[68:71], v[32:47]
	v_sub_f32_e32 v69, v101, v243
	v_sub_f32_e32 v68, v100, v243
	ds_read_b64_tr_b16 v[100:101], v126 offset:0x1600
	v_sub_f32_e32 v71, v103, v243
	v_sub_f32_e32 v70, v102, v243
	ds_read_b64_tr_b16 v[102:103], v126 offset:0x1e00
	v_exp_f32_e32 v64, v64
	v_mfma_f32_32x32x16_bf16 v[32:47], v[76:79], v[122:125], v[32:47]
	v_sub_f32_e32 v124, v109, v243
	v_sub_f32_e32 v125, v108, v243
	v_sub_f32_e32 v122, v111, v243
	v_sub_f32_e32 v123, v110, v243
	v_exp_f32_e32 v65, v65
	v_exp_f32_e32 v66, v66
	v_exp_f32_e32 v67, v67
	v_mfma_f32_32x32x16_bf16 v[32:47], v[112:115], v[198:201], v[32:47]
	v_sub_f32_e32 v199, v105, v243
	v_sub_f32_e32 v200, v104, v243
	ds_read_b64_tr_b16 v[104:105], v126 offset:0x2600
	v_sub_f32_e32 v198, v106, v243
	ds_read_b64_tr_b16 v[106:107], v126 offset:0x2e00
	ds_read_b64_tr_b16 v[108:109], v126 offset:0x3600
	v_exp_f32_e32 v68, v68
	v_exp_f32_e32 v69, v69
	v_exp_f32_e32 v70, v70
	v_exp_f32_e32 v71, v71
	ds_read_b64_tr_b16 v[110:111], v126 offset:0x3e00
	s_waitcnt lgkmcnt(0)
	v_sub_f32_e32 v95, v95, v243
	v_sub_f32_e32 v94, v94, v243
	v_sub_f32_e32 v93, v93, v243
	v_sub_f32_e32 v92, v92, v243
	v_sub_f32_e32 v91, v91, v243
	v_sub_f32_e32 v90, v90, v243
	v_sub_f32_e32 v89, v89, v243
	v_sub_f32_e32 v88, v88, v243
	v_sub_f32_e32 v87, v87, v243
	v_sub_f32_e32 v86, v86, v243
	v_sub_f32_e32 v85, v85, v243
	v_sub_f32_e32 v84, v84, v243
	v_sub_f32_e32 v83, v83, v243
	v_sub_f32_e32 v82, v82, v243
	v_sub_f32_e32 v81, v81, v243
	v_sub_f32_e32 v80, v80, v243
	v_mfma_f32_32x32x16_bf16 v[16:31], v[116:119], v[96:99], v[16:31]
	v_cmp_gt_f32_e32 vcc, 1.0, v244
	v_mfma_f32_32x32x16_bf16 v[16:31], v[72:75], v[100:103], v[16:31]
	v_exp_f32_e32 v72, v200
	v_exp_f32_e32 v73, v199
	v_exp_f32_e32 v74, v198
	v_exp_f32_e32 v75, v127
	v_mfma_f32_32x32x16_bf16 v[16:31], v[76:79], v[104:107], v[16:31]
	v_exp_f32_e32 v76, v125
	v_exp_f32_e32 v77, v124
	v_exp_f32_e32 v78, v123
	v_exp_f32_e32 v79, v122
	v_mfma_f32_32x32x16_bf16 v[16:31], v[112:115], v[108:111], v[16:31]
	s_cbranch_vccz .LBB0_620
	s_and_saveexec_b64 s[74:75], s[0:1]
	ds_write_b32 v179, v244 offset:128
	s_or_b64 exec, exec, s[74:75]
	s_waitcnt lgkmcnt(0)
	v_add_u32_e32 v108, s81, v178
	ds_read_b128 v[96:99], v108 offset:224
	ds_read_b128 v[100:103], v108 offset:192
	ds_read_b128 v[104:107], v108 offset:160
	ds_read_b128 v[108:111], v108 offset:128
	s_waitcnt lgkmcnt(0)
	v_pk_mul_f32 v[12:13], v[12:13], v[96:97]
	v_pk_mul_f32 v[8:9], v[8:9], v[100:101]
	v_pk_mul_f32 v[4:5], v[4:5], v[104:105]
	v_pk_mul_f32 v[14:15], v[14:15], v[98:99]
	v_pk_mul_f32 v[10:11], v[10:11], v[102:103]
	v_pk_mul_f32 v[6:7], v[6:7], v[106:107]
	v_pk_mul_f32 v[2:3], v[2:3], v[110:111]
	v_pk_mul_f32 v[0:1], v[0:1], v[108:109]
	v_pk_mul_f32 v[60:61], v[60:61], v[96:97]
	v_pk_mul_f32 v[56:57], v[56:57], v[100:101]
	v_pk_mul_f32 v[52:53], v[52:53], v[104:105]
	v_pk_mul_f32 v[62:63], v[62:63], v[98:99]
	v_pk_mul_f32 v[58:59], v[58:59], v[102:103]
	v_pk_mul_f32 v[54:55], v[54:55], v[106:107]
	v_pk_mul_f32 v[50:51], v[50:51], v[110:111]
	v_pk_mul_f32 v[48:49], v[48:49], v[108:109]
	v_pk_mul_f32 v[44:45], v[44:45], v[96:97]
	v_pk_mul_f32 v[40:41], v[40:41], v[100:101]
	v_pk_mul_f32 v[36:37], v[36:37], v[104:105]
	v_pk_mul_f32 v[46:47], v[46:47], v[98:99]
	v_pk_mul_f32 v[42:43], v[42:43], v[102:103]
	v_pk_mul_f32 v[38:39], v[38:39], v[106:107]
	v_pk_mul_f32 v[34:35], v[34:35], v[110:111]
	v_pk_mul_f32 v[32:33], v[32:33], v[108:109]
	v_pk_mul_f32 v[28:29], v[28:29], v[96:97]
	v_pk_mul_f32 v[24:25], v[24:25], v[100:101]
	v_pk_mul_f32 v[20:21], v[20:21], v[104:105]
	v_pk_mul_f32 v[30:31], v[30:31], v[98:99]
	v_pk_mul_f32 v[26:27], v[26:27], v[102:103]
	v_pk_mul_f32 v[22:23], v[22:23], v[106:107]
	v_pk_mul_f32 v[18:19], v[18:19], v[110:111]
	v_pk_mul_f32 v[16:17], v[16:17], v[108:109]

; #define LAS __attribute__((address_space(3)))
; __device__ __forceinline__ void finishSM(f32x16& p0, f32x16& p1, float alpha, float& l_reg, bf16x8& pa0, bf16x8& pa1, bf16x8& pa2, bf16x8& pa3) {
; #pragma unroll
;     for (int r = 0; r < 16; ++r) p1[r] = __builtin_amdgcn_exp2f(p1[r]);
;     typedef float f32x2 __attribute__((ext_vector_type(2)));
;     f32x2 s2 = (f32x2){p0[0], p0[1]};
; #pragma unroll
;     for (int r = 2; r < 16; r += 2) s2 += (f32x2){p0[r], p0[r + 1]};
; #pragma unroll
;     for (int r = 0; r < 16; r += 2) s2 += (f32x2){p1[r], p1[r + 1]};
;     float ps = s2.x + s2.y;
;     { auto rr = __builtin_amdgcn_permlane32_swap(__float_as_uint(ps), __float_as_uint(ps), false, false);
;       ps = __uint_as_float(rr[0]) + __uint_as_float(rr[1]); }
;     l_reg = l_reg * alpha + ps;
;     ...
;     PK4(p0, 0, pa0); PK4(p0, 8, pa1); PK4(p1, 0, pa2); PK4(p1, 8, pa3);
;     ...
; }
; template <int MODE> __device__ __forceinline__ void qkt(f32x16& p0, f32x16& p1, const LAS unsigned char* Kt, const LAS unsigned char* Krt, const bf16x8* qr, int r32, int hi, int comp) {
;     p0 = f32x16{}; p1 = f32x16{};
;     constexpr int NDN = MODE ? 8 : 4;
; #pragma unroll
;     for (int d0 = 0; d0 < NDN; ++d0) { const int cb = ((MODE ? 0 : comp * 64) + d0 * 16 + hi * 8) * 2;
;         const bf16x8 b0 = *(const LAS bf16x8*)(Kt + KSWZ(r32, cb));
;         const bf16x8 b1 = *(const LAS bf16x8*)(Kt + KSWZ(32 + r32, cb));
;         p0 = __builtin_amdgcn_mfma_f32_32x32x16_bf16(b0, qr[d0], p0, 0, 0, 0);
;         p1 = __builtin_amdgcn_mfma_f32_32x32x16_bf16(b1, qr[d0], p1, 0, 0, 0); }
;     if constexpr (MODE == 1) {
; #pragma unroll
;         for (int d0 = 0; d0 < 4; ++d0) { const int cb = (d0 * 16 + hi * 8) * 2;
;             const bf16x8 b0 = *(const LAS bf16x8*)(Krt + KRSWZ(r32, cb));
;             const bf16x8 b1 = *(const LAS bf16x8*)(Krt + KRSWZ(32 + r32, cb));
;             p0 = __builtin_amdgcn_mfma_f32_32x32x16_bf16(b0, qr[8 + d0], p0, 0, 0, 0);
;             p1 = __builtin_amdgcn_mfma_f32_32x32x16_bf16(b1, qr[8 + d0], p1, 0, 0, 0); }
;     }
; }
.LBB0_632:
	v_add_u32_e32 v234, v229, v210
	v_add_u32_e32 v235, v229, v212
	v_add_u32_e32 v236, v229, v214
	v_add_u32_e32 v237, v229, v216
	v_add_u32_e32 v238, v229, v218
	v_add_u32_e32 v239, v230, v220
	v_add_u32_e32 v241, v230, v222
	v_add_u32_e32 v240, v230, v224
	ds_read_b128 v[96:99], v231
	ds_read_b128 v[100:103], v231 offset:8192
	v_exp_f32_e32 v80, v80
	v_exp_f32_e32 v81, v81
	v_exp_f32_e32 v82, v82
	s_waitcnt lgkmcnt(0)
	v_mfma_f32_32x32x16_bf16 v[112:127], v[96:99], v[172:175], 0
	v_exp_f32_e32 v83, v83
	v_exp_f32_e32 v84, v84
	v_exp_f32_e32 v85, v85
	v_exp_f32_e32 v86, v86
	v_exp_f32_e32 v87, v87
	v_exp_f32_e32 v88, v88
	v_exp_f32_e32 v89, v89
	v_mfma_f32_32x32x16_bf16 v[96:111], v[100:103], v[172:175], 0
	ds_read_b128 v[172:175], v232
	ds_read_b128 v[182:185], v232 offset:8192
	v_exp_f32_e32 v90, v90
	v_exp_f32_e32 v91, v91
	v_exp_f32_e32 v92, v92
	v_exp_f32_e32 v93, v93
	v_exp_f32_e32 v94, v94
	v_exp_f32_e32 v95, v95
	s_waitcnt lgkmcnt(0)
	v_mfma_f32_32x32x16_bf16 v[112:127], v[172:175], v[168:171], v[112:127]
	v_mfma_f32_32x32x16_bf16 v[96:111], v[182:185], v[168:171], v[96:111]
	ds_read_b128 v[168:171], v233
	ds_read_b128 v[172:175], v233 offset:8192
	s_waitcnt lgkmcnt(0)
	v_mfma_f32_32x32x16_bf16 v[112:127], v[168:171], v[164:167], v[112:127]
	v_mfma_f32_32x32x16_bf16 v[96:111], v[172:175], v[164:167], v[96:111]
	ds_read_b128 v[164:167], v234
	ds_read_b128 v[168:171], v234 offset:8192
	s_waitcnt lgkmcnt(0)
	v_mfma_f32_32x32x16_bf16 v[112:127], v[164:167], v[160:163], v[112:127]
	v_mfma_f32_32x32x16_bf16 v[96:111], v[168:171], v[160:163], v[96:111]
	ds_read_b128 v[160:163], v235
	ds_read_b128 v[164:167], v235 offset:8192
	s_waitcnt lgkmcnt(0)
	v_mfma_f32_32x32x16_bf16 v[112:127], v[160:163], v[156:159], v[112:127]
	v_mfma_f32_32x32x16_bf16 v[96:111], v[164:167], v[156:159], v[96:111]
	ds_read_b128 v[156:159], v236
	ds_read_b128 v[160:163], v236 offset:8192
	s_waitcnt lgkmcnt(0)
	v_mfma_f32_32x32x16_bf16 v[112:127], v[156:159], v[152:155], v[112:127]
	v_mfma_f32_32x32x16_bf16 v[96:111], v[160:163], v[152:155], v[96:111]
	ds_read_b128 v[152:155], v237
	ds_read_b128 v[156:159], v237 offset:8192
	s_waitcnt lgkmcnt(0)
	v_mfma_f32_32x32x16_bf16 v[112:127], v[152:155], v[148:151], v[112:127]
	ds_read_b128 v[152:155], v238
	ds_read_b128 v[160:163], v238 offset:8192
	ds_read_b128 v[164:167], v239
	ds_read_b128 v[168:171], v239 offset:4096
	ds_read_b128 v[172:175], v241
	ds_read_b128 v[182:185], v241 offset:4096
	v_mfma_f32_32x32x16_bf16 v[96:111], v[156:159], v[148:151], v[96:111]
	ds_read_b128 v[148:151], v240
	ds_read_b128 v[156:159], v240 offset:4096
	ds_read_b128 v[186:189], v242
	ds_read_b128 v[190:193], v242 offset:4096
	s_waitcnt lgkmcnt(0)
	v_mfma_f32_32x32x16_bf16 v[112:127], v[152:155], v[144:147], v[112:127]
	v_mfma_f32_32x32x16_bf16 v[96:111], v[160:163], v[144:147], v[96:111]
	v_add_f32_e64 v144, v64, v66
	v_add_f32_e64 v145, v65, v67
	v_add_f32_e64 v144, v68, v144
	v_add_f32_e64 v145, v69, v145
	v_add_f32_e64 v144, v70, v144
	v_add_f32_e64 v145, v71, v145
	v_pk_add_f32 v[144:145], v[72:73], v[144:145]
	v_mfma_f32_32x32x16_bf16 v[112:127], v[164:167], v[140:143], v[112:127]
	v_add_f32_e64 v144, v74, v144
	v_add_f32_e64 v145, v75, v145
	v_add_f32_e64 v144, v76, v144
	v_add_f32_e64 v145, v77, v145
	v_add_f32_e64 v144, v78, v144
	v_add_f32_e64 v145, v79, v145
	v_pk_add_f32 v[144:145], v[80:81], v[144:145]
	v_mfma_f32_32x32x16_bf16 v[96:111], v[168:171], v[140:143], v[96:111]
	v_add_f32_e64 v140, v82, v144
	v_add_f32_e64 v141, v83, v145
	v_add_f32_e64 v140, v84, v140
	v_add_f32_e64 v141, v85, v141
	v_add_f32_e64 v140, v86, v140
	v_add_f32_e64 v141, v87, v141
	v_pk_add_f32 v[140:141], v[88:89], v[140:141]
	v_mfma_f32_32x32x16_bf16 v[112:127], v[172:175], v[136:139], v[112:127]
	v_add_f32_e64 v140, v90, v140
	v_add_f32_e64 v141, v91, v141
	v_add_f32_e64 v140, v92, v140
	v_add_f32_e64 v141, v93, v141
	v_add_f32_e64 v140, v94, v140
	v_add_f32_e64 v141, v95, v141
	v_pk_add_f32 v[144:145], v[140:141], v[140:141] op_sel:[0,1] op_sel_hi:[1,0]
	v_mfma_f32_32x32x16_bf16 v[96:111], v[182:185], v[136:139], v[96:111]
	v_mov_b32_e32 v145, v144
	v_cvt_pk_bf16_f32 v140, v64, v65
	v_cvt_pk_bf16_f32 v141, v66, v67
	v_cvt_pk_bf16_f32 v142, v68, v69
	v_cvt_pk_bf16_f32 v143, v70, v71
	v_cvt_pk_bf16_f32 v72, v72, v73
	v_cvt_pk_bf16_f32 v73, v74, v75
	v_mfma_f32_32x32x16_bf16 v[112:127], v[148:151], v[132:135], v[112:127]
	v_cvt_pk_bf16_f32 v74, v76, v77
	v_cvt_pk_bf16_f32 v75, v78, v79
	v_cvt_pk_bf16_f32 v76, v80, v81
	v_cvt_pk_bf16_f32 v77, v82, v83
	v_cvt_pk_bf16_f32 v78, v84, v85
	v_cvt_pk_bf16_f32 v79, v86, v87
	s_nop 0
	v_permlane32_swap_b32_e32 v144, v145
	v_mfma_f32_32x32x16_bf16 v[96:111], v[156:159], v[132:135], v[96:111]
	v_cvt_pk_bf16_f32 v132, v88, v89
	v_cvt_pk_bf16_f32 v133, v90, v91
	v_cvt_pk_bf16_f32 v134, v92, v93
	v_cvt_pk_bf16_f32 v135, v94, v95
	v_mfma_f32_32x32x16_bf16 v[112:127], v[186:189], v[128:131], v[112:127]
	v_mfma_f32_32x32x16_bf16 v[96:111], v[190:193], v[128:131], v[96:111]
	s_and_b64 vcc, exec, s[4:5]
	s_cbranch_vccnz .LBB0_634
	s_waitcnt vmcnt(0) lgkmcnt(0)
	s_barrier

; __device__ __forceinline__ float sigmoidf_(float x) { return __builtin_amdgcn_rcpf(1.0f + __builtin_amdgcn_exp2f(-x * LOG2E)); }
; __device__ __forceinline__ u32x4 pack8(f32x4 v0, f32x4 v1) { u32x4 w; w.x = cvt_pk_bf16(v0[0], v0[1]); w.y = cvt_pk_bf16(v0[2], v0[3]); w.z = cvt_pk_bf16(v1[0], v1[1]); w.w = cvt_pk_bf16(v1[2], v1[3]); return w; }
;     __device__ __forceinline__ void operator()(AccRef acc, const pg8::Unit& u, int wr, int wc, int fr, int fq) const {
;         const int pn = u.pn, row0 = u.pm * 256 + wr * 64 + fr, cl = wc * 32 + 8 * fq;
; #pragma unroll
;         for (int ai = 0; ai < 2; ++ai)
; #pragma unroll
;             for (int m = 0; m < 4; ++m) {
;                 const int row = row0 + ai * 128 + m * 16;
;                 const float rs = rstd[row];
;                 f32x4 a[2];
; #pragma unroll
;                 for (int n = 0; n < 2; ++n) { const f32x4 gt = acc[ai][0][m][n] * rs, up = acc[ai][1][m][n] * rs;
; #pragma unroll
;                     for (int e = 0; e < 4; ++e) a[n][e] = gt[e] * sigmoidf_(gt[e]) * up[e]; }
;                 *(u32x4*)(ACT + (size_t)row * FF + pn * 128 + cl) = pack8(a[0], a[1]);
;             }
;     }
.LBB0_1113:
	v_lshl_add_u32 v146, s38, 8, v150
	v_ashrrev_i32_e32 v147, 31, v146
	v_lshl_add_u64 v[148:149], v[146:147], 2, s[12:13]
	global_load_dword v200, v[148:149], off
	global_load_dword v202, v[148:149], off offset:64
	global_load_dword v204, v[148:149], off offset:128
	global_load_dword v206, v[148:149], off offset:192
	global_load_dword v208, v[148:149], off offset:512
	global_load_dword v210, v[148:149], off offset:576
	global_load_dword v212, v[148:149], off offset:640
	global_load_dword v214, v[148:149], off offset:704
	v_mov_b32_e32 v161, v114
	v_mov_b32_e32 v114, v123
	v_mov_b32_e32 v158, v124
	v_mov_b32_e32 v159, v116
	v_mov_b32_e32 v116, v125
	v_mov_b32_e32 v124, v126
	v_mov_b32_e32 v125, v118
	v_mov_b32_e32 v118, v127
	v_mov_b32_e32 v126, v120
	v_mov_b32_e32 v127, v112
	v_mov_b32_e32 v112, v121
	v_mov_b32_e32 v160, v122
	v_or_b32_e32 v162, 16, v146
	v_ashrrev_i32_e32 v163, 31, v162
	v_lshl_add_u64 v[164:165], v[162:163], 2, s[12:13]
	s_lshl_b32 s38, s39, 7
	v_mov_b64_e32 v[120:121], s[14:15]
	s_ashr_i32 s39, s38, 31
	v_mad_i64_i32 v[122:123], s[16:17], v146, s56, v[120:121]
	s_lshl_b64 s[38:39], s[38:39], 1
	v_lshl_add_u64 v[122:123], v[122:123], 0, s[38:39]
	v_lshl_add_u64 v[122:123], v[122:123], 0, v[136:137]
	s_andn2_b64 vcc, exec, s[4:5]
	s_mov_b64 s[4:5], -1
	s_waitcnt vmcnt(0)
	v_pk_mul_f32 v[114:115], v[114:115], v[200:201] op_sel_hi:[1,0]
	v_pk_mul_f32 v[158:159], v[158:159], v[200:201] op_sel_hi:[1,0]
	v_pk_mul_f32 v[116:117], v[116:117], v[200:201] op_sel_hi:[1,0]
	v_pk_mul_f32 v[124:125], v[124:125], v[200:201] op_sel_hi:[1,0]
	v_pk_mul_f32 v[118:119], v[118:119], v[200:201] op_sel_hi:[1,0]
	v_pk_mul_f32 v[126:127], v[126:127], v[200:201] op_sel_hi:[1,0]
	v_pk_mul_f32 v[112:113], v[112:113], v[200:201] op_sel_hi:[1,0]
	v_pk_mul_f32 v[160:161], v[160:161], v[200:201] op_sel_hi:[1,0]
	v_mul_f32_e32 v168, 0xbfb8aa3b, v115
	v_mul_f32_e32 v147, 0xbfb8aa3b, v159
	v_mul_f32_e32 v155, 0xbfb8aa3b, v117
	v_mul_f32_e32 v156, 0xbfb8aa3b, v125
	v_mul_f32_e32 v157, 0xbfb8aa3b, v119
	v_mul_f32_e32 v163, 0xbfb8aa3b, v127
	v_mul_f32_e32 v166, 0xbfb8aa3b, v113
	v_mul_f32_e32 v167, 0xbfb8aa3b, v161
	v_exp_f32_e32 v168, v168
	v_exp_f32_e32 v147, v147
	v_exp_f32_e32 v155, v155
	v_exp_f32_e32 v156, v156
	v_exp_f32_e32 v157, v157
	v_exp_f32_e32 v163, v163
	v_exp_f32_e32 v166, v166
	v_exp_f32_e32 v167, v167
	v_add_f32_e32 v168, 1.0, v168
	v_add_f32_e32 v147, 1.0, v147
	v_add_f32_e32 v155, 1.0, v155
	v_add_f32_e32 v156, 1.0, v156
	v_add_f32_e32 v157, 1.0, v157
	v_add_f32_e32 v163, 1.0, v163
	v_add_f32_e32 v166, 1.0, v166
	v_add_f32_e32 v167, 1.0, v167
	v_rcp_f32_e32 v168, v168
	v_rcp_f32_e32 v147, v147
	v_rcp_f32_e32 v155, v155
	v_rcp_f32_e32 v156, v156
	v_rcp_f32_e32 v157, v157
	v_rcp_f32_e32 v163, v163
	v_rcp_f32_e32 v166, v166
	v_rcp_f32_e32 v167, v167
	v_mul_f32_e32 v115, v115, v168
	v_mul_f32_e32 v147, v159, v147
	v_mul_f32_e32 v117, v117, v155
	v_mul_f32_e32 v125, v125, v156
	v_mul_f32_e32 v119, v119, v157
	v_mul_f32_e32 v127, v127, v163
	v_mul_f32_e32 v113, v113, v166
	v_mul_f32_e32 v155, v161, v167
	v_mul_f32_e32 v115, v114, v115
	v_mul_f32_e32 v147, v158, v147
	v_mul_f32_e32 v116, v116, v117
	v_mul_f32_e32 v117, v124, v125
	v_mul_f32_e32 v118, v118, v119
	v_mul_f32_e32 v119, v126, v127
	v_mul_f32_e32 v124, v112, v113
	v_mul_f32_e32 v125, v160, v155
	v_cvt_pk_bf16_f32 v112, v147, v116
	v_cvt_pk_bf16_f32 v113, v117, v118
	v_cvt_pk_bf16_f32 v114, v119, v124
	v_cvt_pk_bf16_f32 v115, v125, v115
	global_store_dwordx4 v[122:123], v[112:115], off
	s_nop 0
	v_mad_i64_i32 v[116:117], s[16:17], v162, s56, v[120:121]
	v_mov_b32_e32 v115, v104
	v_mov_b32_e32 v104, v109
	v_mov_b32_e32 v109, v106
	v_mov_b32_e32 v106, v111
	v_mov_b32_e32 v111, v96
	v_mov_b32_e32 v96, v101
	v_mov_b32_e32 v101, v98
	v_mov_b32_e32 v98, v103
	v_mov_b32_e32 v114, v108
	v_mov_b32_e32 v108, v110
	v_mov_b32_e32 v110, v100
	v_mov_b32_e32 v100, v102
	v_or_b32_e32 v102, 32, v146
	v_ashrrev_i32_e32 v103, 31, v102
	v_lshl_add_u64 v[118:119], v[102:103], 2, s[12:13]
	v_lshl_add_u64 v[116:117], v[116:117], 0, s[38:39]
	v_lshl_add_u64 v[116:117], v[116:117], 0, v[136:137]
	s_nop 0
	v_pk_mul_f32 v[98:99], v[98:99], v[202:203] op_sel_hi:[1,0]
	v_pk_mul_f32 v[114:115], v[114:115], v[202:203] op_sel_hi:[1,0]
	v_pk_mul_f32 v[104:105], v[104:105], v[202:203] op_sel_hi:[1,0]
	v_pk_mul_f32 v[108:109], v[108:109], v[202:203] op_sel_hi:[1,0]
	v_pk_mul_f32 v[106:107], v[106:107], v[202:203] op_sel_hi:[1,0]
	v_pk_mul_f32 v[110:111], v[110:111], v[202:203] op_sel_hi:[1,0]
	v_pk_mul_f32 v[96:97], v[96:97], v[202:203] op_sel_hi:[1,0]
	v_pk_mul_f32 v[100:101], v[100:101], v[202:203] op_sel_hi:[1,0]
	v_mul_f32_e32 v126, 0xbfb8aa3b, v99
	v_mul_f32_e32 v103, 0xbfb8aa3b, v115
	v_mul_f32_e32 v112, 0xbfb8aa3b, v105
	v_mul_f32_e32 v113, 0xbfb8aa3b, v109
	v_mul_f32_e32 v122, 0xbfb8aa3b, v107
	v_mul_f32_e32 v123, 0xbfb8aa3b, v111
	v_mul_f32_e32 v124, 0xbfb8aa3b, v97
	v_mul_f32_e32 v125, 0xbfb8aa3b, v101
	v_exp_f32_e32 v126, v126
	v_exp_f32_e32 v103, v103
	v_exp_f32_e32 v112, v112
	v_exp_f32_e32 v113, v113
	v_exp_f32_e32 v122, v122
	v_exp_f32_e32 v123, v123
	v_exp_f32_e32 v124, v124
	v_exp_f32_e32 v125, v125
	v_add_f32_e32 v126, 1.0, v126
	v_add_f32_e32 v103, 1.0, v103
	v_add_f32_e32 v112, 1.0, v112
	v_add_f32_e32 v113, 1.0, v113
	v_add_f32_e32 v122, 1.0, v122
	v_add_f32_e32 v123, 1.0, v123
	v_add_f32_e32 v124, 1.0, v124
	v_add_f32_e32 v125, 1.0, v125
	v_rcp_f32_e32 v126, v126
	v_rcp_f32_e32 v103, v103
	v_rcp_f32_e32 v112, v112
	v_rcp_f32_e32 v113, v113
	v_rcp_f32_e32 v122, v122
	v_rcp_f32_e32 v123, v123
	v_rcp_f32_e32 v124, v124
	v_rcp_f32_e32 v125, v125
	v_mul_f32_e32 v99, v99, v126
; __device__ __forceinline__ float sigmoidf_(float x) { return __builtin_amdgcn_rcpf(1.0f + __builtin_amdgcn_exp2f(-x * LOG2E)); }
; __device__ __forceinline__ u32x4 pack8(f32x4 v0, f32x4 v1) { u32x4 w; w.x = cvt_pk_bf16(v0[0], v0[1]); w.y = cvt_pk_bf16(v0[2], v0[3]); w.z = cvt_pk_bf16(v1[0], v1[1]); w.w = cvt_pk_bf16(v1[2], v1[3]); return w; }
;     __device__ __forceinline__ void operator()(AccRef acc, const pg8::Unit& u, int wr, int wc, int fr, int fq) const {
;         const int pn = u.pn, row0 = u.pm * 256 + wr * 64 + fr, cl = wc * 32 + 8 * fq;
; #pragma unroll
;         for (int ai = 0; ai < 2; ++ai)
; #pragma unroll
;             for (int m = 0; m < 4; ++m) {
;                 const int row = row0 + ai * 128 + m * 16;
;                 const float rs = rstd[row];
;                 f32x4 a[2];
; #pragma unroll
;                 for (int n = 0; n < 2; ++n) { const f32x4 gt = acc[ai][0][m][n] * rs, up = acc[ai][1][m][n] * rs;
; #pragma unroll
;                     for (int e = 0; e < 4; ++e) a[n][e] = gt[e] * sigmoidf_(gt[e]) * up[e]; }
;                 *(u32x4*)(ACT + (size_t)row * FF + pn * 128 + cl) = pack8(a[0], a[1]);
;             }
;     }
	v_mul_f32_e32 v103, v115, v103
	v_mul_f32_e32 v105, v105, v112
	v_mul_f32_e32 v109, v109, v113
	v_mul_f32_e32 v107, v107, v122
	v_mul_f32_e32 v111, v111, v123
	v_mul_f32_e32 v97, v97, v124
	v_mul_f32_e32 v101, v101, v125
	v_mul_f32_e32 v99, v98, v99
	v_mul_f32_e32 v103, v114, v103
	v_mul_f32_e32 v104, v104, v105
	v_mul_f32_e32 v105, v108, v109
	v_mul_f32_e32 v106, v106, v107
	v_mul_f32_e32 v107, v110, v111
	v_mul_f32_e32 v108, v96, v97
	v_mul_f32_e32 v100, v100, v101
	v_cvt_pk_bf16_f32 v96, v103, v104
	v_cvt_pk_bf16_f32 v97, v105, v106
	v_cvt_pk_bf16_f32 v98, v107, v108
	v_cvt_pk_bf16_f32 v99, v100, v99
	global_store_dwordx4 v[116:117], v[96:99], off
	s_nop 0
	v_mad_i64_i32 v[100:101], s[16:17], v102, s56, v[120:121]
	v_mov_b32_e32 v99, v88
	v_mov_b32_e32 v88, v93
	v_mov_b32_e32 v93, v90
	v_mov_b32_e32 v90, v95
	v_mov_b32_e32 v95, v80
	v_mov_b32_e32 v80, v85
	v_mov_b32_e32 v85, v82
	v_mov_b32_e32 v82, v87
	v_mov_b32_e32 v98, v92
	v_mov_b32_e32 v92, v94
	v_mov_b32_e32 v94, v84
	v_mov_b32_e32 v84, v86
	v_or_b32_e32 v86, 48, v146
	v_ashrrev_i32_e32 v87, 31, v86
	v_lshl_add_u64 v[102:103], v[86:87], 2, s[12:13]
	v_lshl_add_u64 v[100:101], v[100:101], 0, s[38:39]
	v_lshl_add_u64 v[100:101], v[100:101], 0, v[136:137]
	s_nop 0
	v_pk_mul_f32 v[82:83], v[82:83], v[204:205] op_sel_hi:[1,0]
	v_pk_mul_f32 v[98:99], v[98:99], v[204:205] op_sel_hi:[1,0]
	v_pk_mul_f32 v[88:89], v[88:89], v[204:205] op_sel_hi:[1,0]
	v_pk_mul_f32 v[92:93], v[92:93], v[204:205] op_sel_hi:[1,0]
	v_pk_mul_f32 v[90:91], v[90:91], v[204:205] op_sel_hi:[1,0]
	v_pk_mul_f32 v[94:95], v[94:95], v[204:205] op_sel_hi:[1,0]
	v_pk_mul_f32 v[80:81], v[80:81], v[204:205] op_sel_hi:[1,0]
	v_pk_mul_f32 v[84:85], v[84:85], v[204:205] op_sel_hi:[1,0]
	v_mul_f32_e32 v108, 0xbfb8aa3b, v83
	v_mul_f32_e32 v87, 0xbfb8aa3b, v99
	v_mul_f32_e32 v96, 0xbfb8aa3b, v89
	v_mul_f32_e32 v97, 0xbfb8aa3b, v93
	v_mul_f32_e32 v104, 0xbfb8aa3b, v91
	v_mul_f32_e32 v105, 0xbfb8aa3b, v95
	v_mul_f32_e32 v106, 0xbfb8aa3b, v81
	v_mul_f32_e32 v107, 0xbfb8aa3b, v85
	v_exp_f32_e32 v108, v108
	v_exp_f32_e32 v87, v87
	v_exp_f32_e32 v96, v96
	v_exp_f32_e32 v97, v97
	v_exp_f32_e32 v104, v104
	v_exp_f32_e32 v105, v105
	v_exp_f32_e32 v106, v106
	v_exp_f32_e32 v107, v107
	v_add_f32_e32 v108, 1.0, v108
	v_add_f32_e32 v87, 1.0, v87
	v_add_f32_e32 v96, 1.0, v96
	v_add_f32_e32 v97, 1.0, v97
	v_add_f32_e32 v104, 1.0, v104
	v_add_f32_e32 v105, 1.0, v105
	v_add_f32_e32 v106, 1.0, v106
	v_add_f32_e32 v107, 1.0, v107
	v_rcp_f32_e32 v108, v108
	v_rcp_f32_e32 v87, v87
	v_rcp_f32_e32 v96, v96
	v_rcp_f32_e32 v97, v97
	v_rcp_f32_e32 v104, v104
	v_rcp_f32_e32 v105, v105
	v_rcp_f32_e32 v106, v106
	v_rcp_f32_e32 v107, v107
	v_mul_f32_e32 v83, v83, v108
	v_mul_f32_e32 v87, v99, v87
	v_mul_f32_e32 v89, v89, v96
	v_mul_f32_e32 v93, v93, v97
	v_mul_f32_e32 v91, v91, v104
	v_mul_f32_e32 v95, v95, v105
	v_mul_f32_e32 v81, v81, v106
	v_mul_f32_e32 v85, v85, v107
	v_mul_f32_e32 v83, v82, v83
	v_mul_f32_e32 v87, v98, v87
	v_mul_f32_e32 v88, v88, v89
	v_mul_f32_e32 v89, v92, v93
	v_mul_f32_e32 v90, v90, v91
	v_mul_f32_e32 v91, v94, v95
	v_mul_f32_e32 v92, v80, v81
	v_mul_f32_e32 v84, v84, v85
	v_cvt_pk_bf16_f32 v80, v87, v88
	v_cvt_pk_bf16_f32 v81, v89, v90
	v_cvt_pk_bf16_f32 v82, v91, v92
	v_cvt_pk_bf16_f32 v83, v84, v83
	global_store_dwordx4 v[100:101], v[80:83], off
	s_nop 0
	s_nop 0
	v_mov_b32_e32 v82, v76
	v_mov_b32_e32 v83, v72
	v_mov_b32_e32 v72, v77
	v_mov_b32_e32 v76, v78
	v_mov_b32_e32 v77, v74
	v_mov_b32_e32 v74, v79
	v_mov_b32_e32 v78, v64
	v_mov_b32_e32 v79, v68
	v_mov_b32_e32 v68, v65
	v_mov_b32_e32 v64, v66
	v_mov_b32_e32 v65, v70
	v_mov_b32_e32 v70, v67
	v_mad_i64_i32 v[66:67], s[16:17], v86, s56, v[120:121]
	v_lshl_add_u64 v[66:67], v[66:67], 0, s[38:39]
	v_lshl_add_u64 v[84:85], v[66:67], 0, v[136:137]
	s_nop 0
	v_pk_mul_f32 v[66:67], v[82:83], v[206:207] op_sel_hi:[1,0]
	v_pk_mul_f32 v[72:73], v[72:73], v[206:207] op_sel_hi:[1,0]
	v_pk_mul_f32 v[76:77], v[76:77], v[206:207] op_sel_hi:[1,0]
	v_pk_mul_f32 v[74:75], v[74:75], v[206:207] op_sel_hi:[1,0]
	v_pk_mul_f32 v[78:79], v[78:79], v[206:207] op_sel_hi:[1,0]
	v_pk_mul_f32 v[68:69], v[68:69], v[206:207] op_sel_hi:[1,0]
	v_pk_mul_f32 v[64:65], v[64:65], v[206:207] op_sel_hi:[1,0]
	v_pk_mul_f32 v[70:71], v[70:71], v[206:207] op_sel_hi:[1,0]
	v_mul_f32_e32 v80, 0xbfb8aa3b, v67
	v_mul_f32_e32 v81, 0xbfb8aa3b, v73
	v_mul_f32_e32 v82, 0xbfb8aa3b, v77
	v_mul_f32_e32 v83, 0xbfb8aa3b, v75
	v_mul_f32_e32 v86, 0xbfb8aa3b, v79
	v_mul_f32_e32 v87, 0xbfb8aa3b, v69
	v_mul_f32_e32 v88, 0xbfb8aa3b, v65
	v_mul_f32_e32 v89, 0xbfb8aa3b, v71
	v_exp_f32_e32 v80, v80
	v_exp_f32_e32 v81, v81
	v_exp_f32_e32 v82, v82
	v_exp_f32_e32 v83, v83
	v_exp_f32_e32 v86, v86
	v_exp_f32_e32 v87, v87
	v_exp_f32_e32 v88, v88
	v_exp_f32_e32 v89, v89
	v_add_f32_e32 v80, 1.0, v80
	v_add_f32_e32 v81, 1.0, v81
	v_add_f32_e32 v82, 1.0, v82
	v_add_f32_e32 v83, 1.0, v83
	v_add_f32_e32 v86, 1.0, v86
	v_add_f32_e32 v87, 1.0, v87
	v_add_f32_e32 v88, 1.0, v88
	v_add_f32_e32 v89, 1.0, v89
	v_rcp_f32_e32 v80, v80
	v_rcp_f32_e32 v81, v81
	v_rcp_f32_e32 v82, v82
	v_rcp_f32_e32 v83, v83
	v_rcp_f32_e32 v86, v86
	v_rcp_f32_e32 v87, v87
	v_rcp_f32_e32 v88, v88
	v_rcp_f32_e32 v89, v89
	v_mul_f32_e32 v67, v67, v80
	v_mul_f32_e32 v73, v73, v81
	v_mul_f32_e32 v77, v77, v82
	v_mul_f32_e32 v75, v75, v83
	v_mul_f32_e32 v79, v79, v86
	v_mul_f32_e32 v69, v69, v87
	v_mul_f32_e32 v65, v65, v88
	v_mul_f32_e32 v71, v71, v89
	v_mul_f32_e32 v66, v66, v67
	v_mul_f32_e32 v67, v72, v73
	v_mul_f32_e32 v72, v76, v77
	v_mul_f32_e32 v73, v74, v75
	v_mul_f32_e32 v74, v78, v79
	v_mul_f32_e32 v68, v68, v69
	v_mul_f32_e32 v69, v64, v65
	v_mul_f32_e32 v70, v70, v71
; __device__ __forceinline__ float sigmoidf_(float x) { return __builtin_amdgcn_rcpf(1.0f + __builtin_amdgcn_exp2f(-x * LOG2E)); }
; __device__ __forceinline__ u32x4 pack8(f32x4 v0, f32x4 v1) { u32x4 w; w.x = cvt_pk_bf16(v0[0], v0[1]); w.y = cvt_pk_bf16(v0[2], v0[3]); w.z = cvt_pk_bf16(v1[0], v1[1]); w.w = cvt_pk_bf16(v1[2], v1[3]); return w; }
;     __device__ __forceinline__ void operator()(AccRef acc, const pg8::Unit& u, int wr, int wc, int fr, int fq) const {
;         const int pn = u.pn, row0 = u.pm * 256 + wr * 64 + fr, cl = wc * 32 + 8 * fq;
; #pragma unroll
;         for (int ai = 0; ai < 2; ++ai)
; #pragma unroll
;             for (int m = 0; m < 4; ++m) {
;                 const int row = row0 + ai * 128 + m * 16;
;                 const float rs = rstd[row];
;                 f32x4 a[2];
; #pragma unroll
;                 for (int n = 0; n < 2; ++n) { const f32x4 gt = acc[ai][0][m][n] * rs, up = acc[ai][1][m][n] * rs;
; #pragma unroll
;                     for (int e = 0; e < 4; ++e) a[n][e] = gt[e] * sigmoidf_(gt[e]) * up[e]; }
;                 *(u32x4*)(ACT + (size_t)row * FF + pn * 128 + cl) = pack8(a[0], a[1]);
;             }
;     }
	v_cvt_pk_bf16_f32 v64, v66, v67
	v_cvt_pk_bf16_f32 v65, v72, v73
	v_cvt_pk_bf16_f32 v66, v74, v68
	v_cvt_pk_bf16_f32 v67, v69, v70
	global_store_dwordx4 v[84:85], v[64:67], off
	s_nop 0
	s_nop 0
	v_mov_b32_e32 v66, v60
	v_mov_b32_e32 v60, v62
	v_mov_b32_e32 v62, v48
	v_mov_b32_e32 v48, v50
	v_add_u32_e32 v50, 0x80, v146
	v_mov_b32_e32 v67, v56
	v_mov_b32_e32 v56, v61
	v_mov_b32_e32 v61, v58
	v_mov_b32_e32 v58, v63
	v_mov_b32_e32 v63, v52
	v_mov_b32_e32 v52, v49
	v_mov_b32_e32 v49, v54
	v_mov_b32_e32 v54, v51
	v_mad_i64_i32 v[50:51], s[16:17], v50, s56, v[120:121]
	v_lshl_add_u64 v[50:51], v[50:51], 0, s[38:39]
	v_lshl_add_u64 v[68:69], v[50:51], 0, v[136:137]
	s_nop 0
	v_pk_mul_f32 v[50:51], v[66:67], v[208:209] op_sel_hi:[1,0]
	v_pk_mul_f32 v[56:57], v[56:57], v[208:209] op_sel_hi:[1,0]
	v_pk_mul_f32 v[60:61], v[60:61], v[208:209] op_sel_hi:[1,0]
	v_pk_mul_f32 v[58:59], v[58:59], v[208:209] op_sel_hi:[1,0]
	v_pk_mul_f32 v[62:63], v[62:63], v[208:209] op_sel_hi:[1,0]
	v_pk_mul_f32 v[52:53], v[52:53], v[208:209] op_sel_hi:[1,0]
	v_pk_mul_f32 v[48:49], v[48:49], v[208:209] op_sel_hi:[1,0]
	v_pk_mul_f32 v[54:55], v[54:55], v[208:209] op_sel_hi:[1,0]
	v_mul_f32_e32 v64, 0xbfb8aa3b, v51
	v_mul_f32_e32 v65, 0xbfb8aa3b, v57
	v_mul_f32_e32 v66, 0xbfb8aa3b, v61
	v_mul_f32_e32 v67, 0xbfb8aa3b, v59
	v_mul_f32_e32 v70, 0xbfb8aa3b, v63
	v_mul_f32_e32 v71, 0xbfb8aa3b, v53
	v_mul_f32_e32 v72, 0xbfb8aa3b, v49
	v_mul_f32_e32 v73, 0xbfb8aa3b, v55
	v_exp_f32_e32 v64, v64
	v_exp_f32_e32 v65, v65
	v_exp_f32_e32 v66, v66
	v_exp_f32_e32 v67, v67
	v_exp_f32_e32 v70, v70
	v_exp_f32_e32 v71, v71
	v_exp_f32_e32 v72, v72
	v_exp_f32_e32 v73, v73
	v_add_f32_e32 v64, 1.0, v64
	v_add_f32_e32 v65, 1.0, v65
	v_add_f32_e32 v66, 1.0, v66
	v_add_f32_e32 v67, 1.0, v67
	v_add_f32_e32 v70, 1.0, v70
	v_add_f32_e32 v71, 1.0, v71
	v_add_f32_e32 v72, 1.0, v72
	v_add_f32_e32 v73, 1.0, v73
	v_rcp_f32_e32 v64, v64
	v_rcp_f32_e32 v65, v65
	v_rcp_f32_e32 v66, v66
	v_rcp_f32_e32 v67, v67
	v_rcp_f32_e32 v70, v70
	v_rcp_f32_e32 v71, v71
	v_rcp_f32_e32 v72, v72
	v_rcp_f32_e32 v73, v73
	v_mul_f32_e32 v51, v51, v64
	v_mul_f32_e32 v57, v57, v65
	v_mul_f32_e32 v61, v61, v66
	v_mul_f32_e32 v59, v59, v67
	v_mul_f32_e32 v63, v63, v70
	v_mul_f32_e32 v53, v53, v71
	v_mul_f32_e32 v49, v49, v72
	v_mul_f32_e32 v55, v55, v73
	v_mul_f32_e32 v50, v50, v51
	v_mul_f32_e32 v51, v56, v57
	v_mul_f32_e32 v56, v60, v61
	v_mul_f32_e32 v57, v58, v59
	v_mul_f32_e32 v58, v62, v63
	v_mul_f32_e32 v52, v52, v53
	v_mul_f32_e32 v53, v48, v49
	v_mul_f32_e32 v54, v54, v55
	v_cvt_pk_bf16_f32 v48, v50, v51
	v_cvt_pk_bf16_f32 v49, v56, v57
	v_cvt_pk_bf16_f32 v50, v58, v52
	v_cvt_pk_bf16_f32 v51, v53, v54
	global_store_dwordx4 v[68:69], v[48:51], off
	s_nop 0
	s_nop 0
	v_mov_b32_e32 v50, v44
	v_mov_b32_e32 v44, v46
	v_mov_b32_e32 v46, v32
	v_mov_b32_e32 v32, v34
	v_add_u32_e32 v34, 0x90, v146
	v_mov_b32_e32 v51, v40
	v_mov_b32_e32 v40, v45
	v_mov_b32_e32 v45, v42
	v_mov_b32_e32 v42, v47
	v_mov_b32_e32 v47, v36
	v_mov_b32_e32 v36, v33
	v_mov_b32_e32 v33, v38
	v_mov_b32_e32 v38, v35
	v_mad_i64_i32 v[34:35], s[16:17], v34, s56, v[120:121]
	v_lshl_add_u64 v[34:35], v[34:35], 0, s[38:39]
	v_lshl_add_u64 v[52:53], v[34:35], 0, v[136:137]
	s_nop 0
	v_pk_mul_f32 v[34:35], v[50:51], v[210:211] op_sel_hi:[1,0]
	v_pk_mul_f32 v[40:41], v[40:41], v[210:211] op_sel_hi:[1,0]
	v_pk_mul_f32 v[44:45], v[44:45], v[210:211] op_sel_hi:[1,0]
	v_pk_mul_f32 v[42:43], v[42:43], v[210:211] op_sel_hi:[1,0]
	v_pk_mul_f32 v[46:47], v[46:47], v[210:211] op_sel_hi:[1,0]
	v_pk_mul_f32 v[36:37], v[36:37], v[210:211] op_sel_hi:[1,0]
	v_pk_mul_f32 v[32:33], v[32:33], v[210:211] op_sel_hi:[1,0]
	v_pk_mul_f32 v[38:39], v[38:39], v[210:211] op_sel_hi:[1,0]
	v_mul_f32_e32 v48, 0xbfb8aa3b, v35
	v_mul_f32_e32 v49, 0xbfb8aa3b, v41
	v_mul_f32_e32 v50, 0xbfb8aa3b, v45
	v_mul_f32_e32 v51, 0xbfb8aa3b, v43
	v_mul_f32_e32 v54, 0xbfb8aa3b, v47
	v_mul_f32_e32 v55, 0xbfb8aa3b, v37
	v_mul_f32_e32 v56, 0xbfb8aa3b, v33
	v_mul_f32_e32 v57, 0xbfb8aa3b, v39
	v_exp_f32_e32 v48, v48
	v_exp_f32_e32 v49, v49
	v_exp_f32_e32 v50, v50
	v_exp_f32_e32 v51, v51
	v_exp_f32_e32 v54, v54
	v_exp_f32_e32 v55, v55
	v_exp_f32_e32 v56, v56
	v_exp_f32_e32 v57, v57
	v_add_f32_e32 v48, 1.0, v48
	v_add_f32_e32 v49, 1.0, v49
	v_add_f32_e32 v50, 1.0, v50
	v_add_f32_e32 v51, 1.0, v51
	v_add_f32_e32 v54, 1.0, v54
	v_add_f32_e32 v55, 1.0, v55
	v_add_f32_e32 v56, 1.0, v56
	v_add_f32_e32 v57, 1.0, v57
	v_rcp_f32_e32 v48, v48
	v_rcp_f32_e32 v49, v49
	v_rcp_f32_e32 v50, v50
	v_rcp_f32_e32 v51, v51
	v_rcp_f32_e32 v54, v54
	v_rcp_f32_e32 v55, v55
	v_rcp_f32_e32 v56, v56
	v_rcp_f32_e32 v57, v57
	v_mul_f32_e32 v35, v35, v48
	v_mul_f32_e32 v41, v41, v49
	v_mul_f32_e32 v45, v45, v50
	v_mul_f32_e32 v43, v43, v51
	v_mul_f32_e32 v47, v47, v54
	v_mul_f32_e32 v37, v37, v55
	v_mul_f32_e32 v33, v33, v56
	v_mul_f32_e32 v39, v39, v57
	v_mul_f32_e32 v34, v34, v35
	v_mul_f32_e32 v35, v40, v41
	v_mul_f32_e32 v40, v44, v45
	v_mul_f32_e32 v41, v42, v43
	v_mul_f32_e32 v42, v46, v47
	v_mul_f32_e32 v36, v36, v37
	v_mul_f32_e32 v37, v32, v33
	v_mul_f32_e32 v38, v38, v39
	v_cvt_pk_bf16_f32 v32, v34, v35
	v_cvt_pk_bf16_f32 v33, v40, v41
	v_cvt_pk_bf16_f32 v34, v42, v36
; __device__ __forceinline__ float sigmoidf_(float x) { return __builtin_amdgcn_rcpf(1.0f + __builtin_amdgcn_exp2f(-x * LOG2E)); }
; __device__ __forceinline__ u32x4 pack8(f32x4 v0, f32x4 v1) { u32x4 w; w.x = cvt_pk_bf16(v0[0], v0[1]); w.y = cvt_pk_bf16(v0[2], v0[3]); w.z = cvt_pk_bf16(v1[0], v1[1]); w.w = cvt_pk_bf16(v1[2], v1[3]); return w; }
;     __device__ __forceinline__ void operator()(AccRef acc, const pg8::Unit& u, int wr, int wc, int fr, int fq) const {
;         const int pn = u.pn, row0 = u.pm * 256 + wr * 64 + fr, cl = wc * 32 + 8 * fq;
; #pragma unroll
;         for (int ai = 0; ai < 2; ++ai)
; #pragma unroll
;             for (int m = 0; m < 4; ++m) {
;                 const int row = row0 + ai * 128 + m * 16;
;                 const float rs = rstd[row];
;                 f32x4 a[2];
; #pragma unroll
;                 for (int n = 0; n < 2; ++n) { const f32x4 gt = acc[ai][0][m][n] * rs, up = acc[ai][1][m][n] * rs;
; #pragma unroll
;                     for (int e = 0; e < 4; ++e) a[n][e] = gt[e] * sigmoidf_(gt[e]) * up[e]; }
;                 *(u32x4*)(ACT + (size_t)row * FF + pn * 128 + cl) = pack8(a[0], a[1]);
;             }
;     }
	v_cvt_pk_bf16_f32 v35, v37, v38
	global_store_dwordx4 v[52:53], v[32:35], off
	s_nop 0
	s_nop 0
	v_mov_b32_e32 v34, v28
	v_mov_b32_e32 v28, v30
	v_mov_b32_e32 v30, v16
	v_mov_b32_e32 v16, v18
	v_add_u32_e32 v18, 0xa0, v146
	v_mov_b32_e32 v35, v24
	v_mov_b32_e32 v24, v29
	v_mov_b32_e32 v29, v26
	v_mov_b32_e32 v26, v31
	v_mov_b32_e32 v31, v20
	v_mov_b32_e32 v20, v17
	v_mov_b32_e32 v17, v22
	v_mov_b32_e32 v22, v19
	v_mad_i64_i32 v[18:19], s[16:17], v18, s56, v[120:121]
	v_lshl_add_u64 v[18:19], v[18:19], 0, s[38:39]
	v_lshl_add_u64 v[36:37], v[18:19], 0, v[136:137]
	s_nop 0
	v_pk_mul_f32 v[18:19], v[34:35], v[212:213] op_sel_hi:[1,0]
	v_pk_mul_f32 v[24:25], v[24:25], v[212:213] op_sel_hi:[1,0]
	v_pk_mul_f32 v[28:29], v[28:29], v[212:213] op_sel_hi:[1,0]
	v_pk_mul_f32 v[26:27], v[26:27], v[212:213] op_sel_hi:[1,0]
	v_pk_mul_f32 v[30:31], v[30:31], v[212:213] op_sel_hi:[1,0]
	v_pk_mul_f32 v[20:21], v[20:21], v[212:213] op_sel_hi:[1,0]
	v_pk_mul_f32 v[16:17], v[16:17], v[212:213] op_sel_hi:[1,0]
	v_pk_mul_f32 v[22:23], v[22:23], v[212:213] op_sel_hi:[1,0]
	v_mul_f32_e32 v32, 0xbfb8aa3b, v19
	v_mul_f32_e32 v33, 0xbfb8aa3b, v25
	v_mul_f32_e32 v34, 0xbfb8aa3b, v29
	v_mul_f32_e32 v35, 0xbfb8aa3b, v27
	v_mul_f32_e32 v38, 0xbfb8aa3b, v31
	v_mul_f32_e32 v39, 0xbfb8aa3b, v21
	v_mul_f32_e32 v40, 0xbfb8aa3b, v17
	v_mul_f32_e32 v41, 0xbfb8aa3b, v23
	v_exp_f32_e32 v32, v32
	v_exp_f32_e32 v33, v33
	v_exp_f32_e32 v34, v34
	v_exp_f32_e32 v35, v35
	v_exp_f32_e32 v38, v38
	v_exp_f32_e32 v39, v39
	v_exp_f32_e32 v40, v40
	v_exp_f32_e32 v41, v41
	v_add_f32_e32 v32, 1.0, v32
	v_add_f32_e32 v33, 1.0, v33
	v_add_f32_e32 v34, 1.0, v34
	v_add_f32_e32 v35, 1.0, v35
	v_add_f32_e32 v38, 1.0, v38
	v_add_f32_e32 v39, 1.0, v39
	v_add_f32_e32 v40, 1.0, v40
	v_add_f32_e32 v41, 1.0, v41
	v_rcp_f32_e32 v32, v32
	v_rcp_f32_e32 v33, v33
	v_rcp_f32_e32 v34, v34
	v_rcp_f32_e32 v35, v35
	v_rcp_f32_e32 v38, v38
	v_rcp_f32_e32 v39, v39
	v_rcp_f32_e32 v40, v40
	v_rcp_f32_e32 v41, v41
	v_mul_f32_e32 v19, v19, v32
	v_mul_f32_e32 v25, v25, v33
	v_mul_f32_e32 v29, v29, v34
	v_mul_f32_e32 v27, v27, v35
	v_mul_f32_e32 v31, v31, v38
	v_mul_f32_e32 v21, v21, v39
	v_mul_f32_e32 v17, v17, v40
	v_mul_f32_e32 v23, v23, v41
	v_mul_f32_e32 v18, v18, v19
	v_mul_f32_e32 v19, v24, v25
	v_mul_f32_e32 v24, v28, v29
	v_mul_f32_e32 v25, v26, v27
	v_mul_f32_e32 v26, v30, v31
	v_mul_f32_e32 v20, v20, v21
	v_mul_f32_e32 v21, v16, v17
	v_mul_f32_e32 v22, v22, v23
	v_cvt_pk_bf16_f32 v16, v18, v19
	v_cvt_pk_bf16_f32 v17, v24, v25
	v_cvt_pk_bf16_f32 v18, v26, v20
	v_cvt_pk_bf16_f32 v19, v21, v22
	global_store_dwordx4 v[36:37], v[16:19], off
	s_nop 0
	s_nop 0
	v_mov_b32_e32 v18, v12
	v_mov_b32_e32 v12, v14
	v_mov_b32_e32 v14, v0
	v_mov_b32_e32 v0, v2
	v_add_u32_e32 v2, 0xb0, v146
	v_mov_b32_e32 v19, v8
	v_mov_b32_e32 v8, v13
	v_mov_b32_e32 v13, v10
	v_mov_b32_e32 v10, v15
	v_mov_b32_e32 v15, v4
	v_mov_b32_e32 v4, v1
	v_mov_b32_e32 v1, v6
	v_mov_b32_e32 v6, v3
	v_mad_i64_i32 v[2:3], s[16:17], v2, s56, v[120:121]
	v_lshl_add_u64 v[2:3], v[2:3], 0, s[38:39]
	v_lshl_add_u64 v[20:21], v[2:3], 0, v[136:137]
	s_nop 0
	v_pk_mul_f32 v[2:3], v[18:19], v[214:215] op_sel_hi:[1,0]
	v_pk_mul_f32 v[8:9], v[8:9], v[214:215] op_sel_hi:[1,0]
	v_pk_mul_f32 v[12:13], v[12:13], v[214:215] op_sel_hi:[1,0]
	v_pk_mul_f32 v[10:11], v[10:11], v[214:215] op_sel_hi:[1,0]
	v_pk_mul_f32 v[14:15], v[14:15], v[214:215] op_sel_hi:[1,0]
	v_pk_mul_f32 v[4:5], v[4:5], v[214:215] op_sel_hi:[1,0]
	v_pk_mul_f32 v[0:1], v[0:1], v[214:215] op_sel_hi:[1,0]
	v_pk_mul_f32 v[6:7], v[6:7], v[214:215] op_sel_hi:[1,0]
	v_mul_f32_e32 v16, 0xbfb8aa3b, v3
	v_mul_f32_e32 v17, 0xbfb8aa3b, v9
	v_mul_f32_e32 v18, 0xbfb8aa3b, v13
	v_mul_f32_e32 v19, 0xbfb8aa3b, v11
	v_mul_f32_e32 v22, 0xbfb8aa3b, v15
	v_mul_f32_e32 v23, 0xbfb8aa3b, v5
	v_mul_f32_e32 v24, 0xbfb8aa3b, v1
	v_mul_f32_e32 v25, 0xbfb8aa3b, v7
	v_exp_f32_e32 v16, v16
	v_exp_f32_e32 v17, v17
	v_exp_f32_e32 v18, v18
	v_exp_f32_e32 v19, v19
	v_exp_f32_e32 v22, v22
	v_exp_f32_e32 v23, v23
	v_exp_f32_e32 v24, v24
	v_exp_f32_e32 v25, v25
	v_add_f32_e32 v16, 1.0, v16
	v_add_f32_e32 v17, 1.0, v17
	v_add_f32_e32 v18, 1.0, v18
	v_add_f32_e32 v19, 1.0, v19
	v_add_f32_e32 v22, 1.0, v22
	v_add_f32_e32 v23, 1.0, v23
	v_add_f32_e32 v24, 1.0, v24
	v_add_f32_e32 v25, 1.0, v25
	v_rcp_f32_e32 v16, v16
	v_rcp_f32_e32 v17, v17
	v_rcp_f32_e32 v18, v18
	v_rcp_f32_e32 v19, v19
	v_rcp_f32_e32 v22, v22
	v_rcp_f32_e32 v23, v23
	v_rcp_f32_e32 v24, v24
	v_rcp_f32_e32 v25, v25
	v_mul_f32_e32 v3, v3, v16
	v_mul_f32_e32 v9, v9, v17
	v_mul_f32_e32 v13, v13, v18
	v_mul_f32_e32 v11, v11, v19
	v_mul_f32_e32 v15, v15, v22
	v_mul_f32_e32 v5, v5, v23
	v_mul_f32_e32 v1, v1, v24
	v_mul_f32_e32 v7, v7, v25
	v_mul_f32_e32 v2, v2, v3
	v_mul_f32_e32 v3, v8, v9
	v_mul_f32_e32 v8, v12, v13
	v_mul_f32_e32 v9, v10, v11
	v_mul_f32_e32 v10, v14, v15
	v_mul_f32_e32 v4, v4, v5
	v_mul_f32_e32 v5, v0, v1
	v_mul_f32_e32 v6, v6, v7
	v_cvt_pk_bf16_f32 v0, v2, v3
	v_cvt_pk_bf16_f32 v1, v8, v9
	v_cvt_pk_bf16_f32 v2, v10, v4
	v_cvt_pk_bf16_f32 v3, v5, v6
	global_store_dwordx4 v[20:21], v[0:3], off
	s_cbranch_vccnz .LBB0_1106
	s_andn2_b64 vcc, exec, s[6:7]
	s_cbranch_vccnz .LBB0_1105
	s_barrier
	s_branch .LBB0_1105
